# A loop: first K-fragment LDS reads of steps 2-4 issued right after the barrier (before the row-sum chain), on top of A SGPR-base DMA restructure
# speedup vs baseline: 1.0022x; 1.0022x over previous
.LBB0_559:
.LBB0_561:
	v_pk_add_f32 v[34:35], v[184:185], v[34:35]
	v_pk_add_f32 v[36:37], v[186:187], v[36:37]
	v_pk_add_f32 v[32:33], v[32:33], v[34:35]
	v_pk_add_f32 v[36:37], v[40:41], v[36:37]
	v_pk_add_f32 v[32:33], v[38:39], v[32:33]
	v_pk_add_f32 v[36:37], v[42:43], v[36:37]
	v_pk_add_f32 v[32:33], v[44:45], v[32:33]
	v_pk_add_f32 v[36:37], v[80:81], v[36:37]
	v_pk_add_f32 v[32:33], v[46:47], v[32:33]
	v_pk_add_f32 v[36:37], v[82:83], v[36:37]
	v_pk_add_f32 v[32:33], v[64:65], v[32:33]
	v_pk_add_f32 v[36:37], v[66:67], v[36:37]
	v_pk_add_f32 v[32:33], v[68:69], v[32:33]
	s_waitcnt lgkmcnt(0)
	s_barrier
	ds_read_b128 v[64:67], v199 offset:40960
	ds_read_b128 v[220:223], v199 offset:45056
	v_pk_add_f32 v[184:185], v[72:73], v[32:33]
	v_max_f32_e32 v32, v76, v76
	v_max_f32_e32 v33, v77, v77
	v_pk_add_f32 v[36:37], v[70:71], v[36:37]
	v_max_f32_e32 v32, v32, v33
	v_pk_add_f32 v[186:187], v[74:75], v[36:37]
	v_cmp_lt_f32_e32 vcc, s96, v32
	s_cbranch_vccz .LBB0_563
	v_max_f32_e32 v32, v32, v32
	v_max_f32_e32 v33, 0, v32
	v_exp_f32_e64 v34, -v33
	v_add_f32_e32 v209, v209, v33
	v_xor_b32_e32 v32, 0x80000000, v209
	v_sub_f32_e32 v127, v127, v33
	v_sub_f32_e32 v126, v126, v33
	v_sub_f32_e32 v125, v125, v33
	v_sub_f32_e32 v124, v124, v33
	v_sub_f32_e32 v123, v123, v33
	v_sub_f32_e32 v122, v122, v33
	v_sub_f32_e32 v121, v121, v33
	v_sub_f32_e32 v120, v120, v33
	v_sub_f32_e32 v119, v119, v33
	v_sub_f32_e32 v118, v118, v33
	v_sub_f32_e32 v117, v117, v33
	v_sub_f32_e32 v116, v116, v33
	v_sub_f32_e32 v115, v115, v33
	v_sub_f32_e32 v114, v114, v33
	v_sub_f32_e32 v113, v113, v33
	v_sub_f32_e32 v112, v112, v33
	v_sub_f32_e32 v111, v111, v33
	v_sub_f32_e32 v110, v110, v33
	v_sub_f32_e32 v109, v109, v33
	v_sub_f32_e32 v108, v108, v33
	v_sub_f32_e32 v107, v107, v33
	v_sub_f32_e32 v106, v106, v33
	v_sub_f32_e32 v105, v105, v33
	v_sub_f32_e32 v104, v104, v33
	v_sub_f32_e32 v103, v103, v33
	v_sub_f32_e32 v102, v102, v33
	v_sub_f32_e32 v101, v101, v33
	v_sub_f32_e32 v100, v100, v33
	v_sub_f32_e32 v99, v99, v33
	v_sub_f32_e32 v98, v98, v33
	v_sub_f32_e32 v97, v97, v33
	v_sub_f32_e32 v96, v96, v33
	v_pk_mul_f32 v[14:15], v[14:15], v[34:35] op_sel_hi:[1,0]
	v_pk_mul_f32 v[12:13], v[12:13], v[34:35] op_sel_hi:[1,0]
	v_pk_mul_f32 v[10:11], v[10:11], v[34:35] op_sel_hi:[1,0]
	v_pk_mul_f32 v[8:9], v[8:9], v[34:35] op_sel_hi:[1,0]
	v_pk_mul_f32 v[6:7], v[6:7], v[34:35] op_sel_hi:[1,0]
	v_pk_mul_f32 v[4:5], v[4:5], v[34:35] op_sel_hi:[1,0]
	v_pk_mul_f32 v[2:3], v[2:3], v[34:35] op_sel_hi:[1,0]
	v_pk_mul_f32 v[0:1], v[0:1], v[34:35] op_sel_hi:[1,0]
	v_pk_mul_f32 v[30:31], v[30:31], v[34:35] op_sel_hi:[1,0]
	v_pk_mul_f32 v[28:29], v[28:29], v[34:35] op_sel_hi:[1,0]
	v_pk_mul_f32 v[26:27], v[26:27], v[34:35] op_sel_hi:[1,0]
	v_pk_mul_f32 v[24:25], v[24:25], v[34:35] op_sel_hi:[1,0]
	v_pk_mul_f32 v[22:23], v[22:23], v[34:35] op_sel_hi:[1,0]
	v_pk_mul_f32 v[20:21], v[20:21], v[34:35] op_sel_hi:[1,0]
	v_pk_mul_f32 v[18:19], v[18:19], v[34:35] op_sel_hi:[1,0]
	v_pk_mul_f32 v[16:17], v[16:17], v[34:35] op_sel_hi:[1,0]
	v_pk_mul_f32 v[184:185], v[184:185], v[34:35] op_sel_hi:[1,0]
	v_pk_mul_f32 v[186:187], v[186:187], v[34:35] op_sel_hi:[1,0]
	v_mov_b32_e32 v33, v32
	v_mov_b32_e32 v34, v32
	v_mov_b32_e32 v35, v32
	v_mov_b32_e32 v36, v32
	v_mov_b32_e32 v37, v32
	v_mov_b32_e32 v38, v32
	v_mov_b32_e32 v39, v32
	v_mov_b32_e32 v40, v32
	v_mov_b32_e32 v41, v32
	v_mov_b32_e32 v42, v32
	v_mov_b32_e32 v43, v32
	v_mov_b32_e32 v44, v32
	v_mov_b32_e32 v45, v32
	v_mov_b32_e32 v46, v32
	v_mov_b32_e32 v47, v32
	v_mov_b32_e32 v48, v32
	v_mov_b32_e32 v49, v32
	v_mov_b32_e32 v50, v32
	v_mov_b32_e32 v51, v32
	v_mov_b32_e32 v52, v32
	v_mov_b32_e32 v53, v32
	v_mov_b32_e32 v54, v32
	v_mov_b32_e32 v55, v32
	v_mov_b32_e32 v56, v32
	v_mov_b32_e32 v57, v32
	v_mov_b32_e32 v58, v32
	v_mov_b32_e32 v59, v32
	v_mov_b32_e32 v60, v32
	v_mov_b32_e32 v61, v32
	v_mov_b32_e32 v62, v32
	v_mov_b32_e32 v63, v32
	s_branch .LBB0_564

.LBB0_564:
.LBB0_566:
	s_add_u32 s4, s92, 0x15658000
	s_addc_u32 s5, s93, 0
	s_mov_b32 m0, s43
	s_nop 0
	global_load_lds_dwordx4 v164, s[4:5]
	s_waitcnt lgkmcnt(0)
	v_mfma_f32_32x32x16_bf16 v[80:95], v[64:67], v[132:135], v[32:47]
	ds_read_b128 v[68:71], v200 offset:40960
	ds_read_b128 v[224:227], v200 offset:45056
	s_setprio 1
	v_exp_f32_e32 v112, v112
	v_exp_f32_e32 v189, v113
	v_exp_f32_e32 v188, v114
	v_exp_f32_e32 v113, v115
	s_setprio 0
	s_add_u32 s4, s92, 0x16618200
	s_addc_u32 s5, s93, 0
	s_mov_b32 m0, s70
	s_nop 0
	global_load_lds_dwordx4 v160, s[4:5]
	s_waitcnt lgkmcnt(0)
	v_mfma_f32_32x32x16_bf16 v[80:95], v[68:71], v[128:131], v[80:95]
	ds_read_b128 v[228:231], v201 offset:40960
	ds_read_b128 v[232:235], v201 offset:45056
	s_setprio 1
	v_mfma_f32_32x32x16_bf16 v[64:79], v[220:223], v[132:135], v[32:47]
	v_exp_f32_e32 v114, v116
	v_exp_f32_e32 v117, v117
	v_exp_f32_e32 v116, v118
	v_exp_f32_e32 v115, v119
	s_setprio 0
	v_cvt_pk_bf16_f32 v220, v112, v189
	v_cvt_pk_bf16_f32 v221, v188, v113
	v_cvt_pk_bf16_f32 v222, v114, v117
	v_cvt_pk_bf16_f32 v223, v116, v115
	s_and_b64 vcc, exec, s[44:45]
	s_cbranch_vccnz .Lmy_a2_norope
	s_add_u32 s4, s92, 0x31d8500
	s_addc_u32 s5, s93, 0
	s_add_i32 m0, s43, 0x4000
	s_nop 0
	global_load_lds_dwordx4 v162, s[4:5]

.LBB0_568:
.LBB0_570:
	v_pk_add_f32 v[126:127], v[186:187], v[188:189]
	v_pk_add_f32 v[112:113], v[112:113], v[184:185]
	v_pk_add_f32 v[116:117], v[116:117], v[126:127]
	v_pk_add_f32 v[112:113], v[114:115], v[112:113]
	v_pk_add_f32 v[116:117], v[190:191], v[116:117]
	v_pk_add_f32 v[112:113], v[118:119], v[112:113]
	v_pk_add_f32 v[114:115], v[122:123], v[116:117]
	s_waitcnt lgkmcnt(0)
	s_barrier
	ds_read_b128 v[166:169], v199 offset:61440
	v_pk_add_f32 v[114:115], v[124:125], v[114:115]
	s_nop 0
	v_pk_add_f32 v[100:101], v[100:101], v[114:115]
	s_nop 0
	v_pk_add_f32 v[100:101], v[104:105], v[100:101]
	v_pk_add_f32 v[104:105], v[120:121], v[112:113]
	v_pk_add_f32 v[186:187], v[108:109], v[100:101]
	v_pk_add_f32 v[96:97], v[96:97], v[104:105]
	s_nop 0
	v_pk_add_f32 v[96:97], v[98:99], v[96:97]
	s_nop 0
	v_pk_add_f32 v[96:97], v[102:103], v[96:97]
	s_nop 0
	v_pk_add_f32 v[184:185], v[106:107], v[96:97]
	v_max_f32_e32 v96, v110, v110
	v_max_f32_e32 v97, v111, v111
	v_max_f32_e32 v96, v96, v97
	v_cmp_lt_f32_e32 vcc, s96, v96
	s_cbranch_vccz .LBB0_572
	v_max_f32_e32 v32, v96, v96
	v_max_f32_e32 v33, 0, v32
	v_exp_f32_e64 v34, -v33
	v_add_f32_e32 v209, v209, v33
	v_xor_b32_e32 v32, 0x80000000, v209
	v_sub_f32_e32 v95, v95, v33
	v_sub_f32_e32 v94, v94, v33
	v_sub_f32_e32 v93, v93, v33
	v_sub_f32_e32 v92, v92, v33
	v_sub_f32_e32 v91, v91, v33
	v_sub_f32_e32 v90, v90, v33
	v_sub_f32_e32 v89, v89, v33
	v_sub_f32_e32 v88, v88, v33
	v_sub_f32_e32 v87, v87, v33
	v_sub_f32_e32 v86, v86, v33
	v_sub_f32_e32 v85, v85, v33
	v_sub_f32_e32 v84, v84, v33
	v_sub_f32_e32 v83, v83, v33
	v_sub_f32_e32 v82, v82, v33
	v_sub_f32_e32 v81, v81, v33
	v_sub_f32_e32 v80, v80, v33
	v_sub_f32_e32 v79, v79, v33
	v_sub_f32_e32 v78, v78, v33
	v_sub_f32_e32 v77, v77, v33
	v_sub_f32_e32 v76, v76, v33
	v_sub_f32_e32 v75, v75, v33
	v_sub_f32_e32 v74, v74, v33
	v_sub_f32_e32 v73, v73, v33
	v_sub_f32_e32 v72, v72, v33
	v_sub_f32_e32 v71, v71, v33
	v_sub_f32_e32 v70, v70, v33
	v_sub_f32_e32 v69, v69, v33
	v_sub_f32_e32 v68, v68, v33
	v_sub_f32_e32 v67, v67, v33
	v_sub_f32_e32 v66, v66, v33
	v_sub_f32_e32 v65, v65, v33
	v_sub_f32_e32 v64, v64, v33
	v_pk_mul_f32 v[14:15], v[14:15], v[34:35] op_sel_hi:[1,0]
	v_pk_mul_f32 v[12:13], v[12:13], v[34:35] op_sel_hi:[1,0]
	v_pk_mul_f32 v[10:11], v[10:11], v[34:35] op_sel_hi:[1,0]
	v_pk_mul_f32 v[8:9], v[8:9], v[34:35] op_sel_hi:[1,0]
	v_pk_mul_f32 v[6:7], v[6:7], v[34:35] op_sel_hi:[1,0]
	v_pk_mul_f32 v[4:5], v[4:5], v[34:35] op_sel_hi:[1,0]
	v_pk_mul_f32 v[2:3], v[2:3], v[34:35] op_sel_hi:[1,0]
	v_pk_mul_f32 v[0:1], v[0:1], v[34:35] op_sel_hi:[1,0]
	v_pk_mul_f32 v[30:31], v[30:31], v[34:35] op_sel_hi:[1,0]
	v_pk_mul_f32 v[28:29], v[28:29], v[34:35] op_sel_hi:[1,0]
	v_pk_mul_f32 v[26:27], v[26:27], v[34:35] op_sel_hi:[1,0]
	v_pk_mul_f32 v[24:25], v[24:25], v[34:35] op_sel_hi:[1,0]
	v_pk_mul_f32 v[22:23], v[22:23], v[34:35] op_sel_hi:[1,0]
	v_pk_mul_f32 v[20:21], v[20:21], v[34:35] op_sel_hi:[1,0]
	v_pk_mul_f32 v[18:19], v[18:19], v[34:35] op_sel_hi:[1,0]
	v_pk_mul_f32 v[16:17], v[16:17], v[34:35] op_sel_hi:[1,0]
	v_pk_mul_f32 v[184:185], v[184:185], v[34:35] op_sel_hi:[1,0]
	v_pk_mul_f32 v[186:187], v[186:187], v[34:35] op_sel_hi:[1,0]
	v_mov_b32_e32 v33, v32
	v_mov_b32_e32 v34, v32
	v_mov_b32_e32 v35, v32
	v_mov_b32_e32 v36, v32
	v_mov_b32_e32 v37, v32
	v_mov_b32_e32 v38, v32
	v_mov_b32_e32 v39, v32
	v_mov_b32_e32 v40, v32
	v_mov_b32_e32 v41, v32
	v_mov_b32_e32 v42, v32
	v_mov_b32_e32 v43, v32
	v_mov_b32_e32 v44, v32
	v_mov_b32_e32 v45, v32
	v_mov_b32_e32 v46, v32
	v_mov_b32_e32 v47, v32
	v_mov_b32_e32 v48, v32
	v_mov_b32_e32 v49, v32
	v_mov_b32_e32 v50, v32
	v_mov_b32_e32 v51, v32
	v_mov_b32_e32 v52, v32
	v_mov_b32_e32 v53, v32
	v_mov_b32_e32 v54, v32
	v_mov_b32_e32 v55, v32
	v_mov_b32_e32 v56, v32
	v_mov_b32_e32 v57, v32
	v_mov_b32_e32 v58, v32
	v_mov_b32_e32 v59, v32
	v_mov_b32_e32 v60, v32
	v_mov_b32_e32 v61, v32
	v_mov_b32_e32 v62, v32
	v_mov_b32_e32 v63, v32
.LBB0_572:
.LBB0_574:
	s_add_i32 s10, 0, 0x10000
	v_add_u32_e32 v172, s10, v212
	ds_read_b128 v[174:177], v172
	s_add_u32 s4, s92, 0x15668000
	s_addc_u32 s5, s93, 0
	s_mov_b32 m0, s71
	s_nop 0
	global_load_lds_dwordx4 v164, s[4:5]
	s_waitcnt lgkmcnt(0)
	v_mfma_f32_32x32x16_bf16 v[112:127], v[166:169], v[132:135], v[32:47]
	v_add_u32_e32 v220, s10, v214
	ds_read_b128 v[100:103], v200 offset:61440
	ds_read_b128 v[180:183], v220
	s_setprio 1
	v_exp_f32_e32 v80, v80
	v_exp_f32_e32 v189, v81
	v_exp_f32_e32 v188, v82
	v_exp_f32_e32 v81, v83
	s_setprio 0
	s_add_u32 s4, s92, 0x16618280
	s_addc_u32 s5, s93, 0
	s_mov_b32 m0, s90
	s_nop 0
	global_load_lds_dwordx4 v160, s[4:5]
	s_waitcnt lgkmcnt(0)
	v_mfma_f32_32x32x16_bf16 v[112:127], v[100:103], v[128:131], v[112:127]
	v_add_u32_e32 v221, s10, v216
	ds_read_b128 v[224:227], v201 offset:61440
	ds_read_b128 v[228:231], v221
	s_setprio 1
	v_mfma_f32_32x32x16_bf16 v[96:111], v[174:177], v[132:135], v[32:47]
	v_exp_f32_e32 v82, v84
	v_exp_f32_e32 v191, v85
	v_exp_f32_e32 v190, v86
	v_exp_f32_e32 v83, v87
	s_setprio 0
	v_cvt_pk_bf16_f32 v174, v80, v189
	v_cvt_pk_bf16_f32 v175, v188, v81
	v_cvt_pk_bf16_f32 v176, v82, v191
	v_cvt_pk_bf16_f32 v177, v190, v83
	s_and_b64 vcc, exec, s[44:45]
	s_cbranch_vccnz .Lmy_a3_norope
	s_add_u32 s4, s92, 0x32c8500
	s_addc_u32 s5, s93, 0
	s_add_i32 m0, s43, 0x9000
	s_nop 0
	global_load_lds_dwordx4 v162, s[4:5]

.LBB0_576:
.LBB0_578:
	v_pk_add_f32 v[80:81], v[80:81], v[184:185]
	v_pk_add_f32 v[94:95], v[186:187], v[188:189]
	v_pk_add_f32 v[80:81], v[82:83], v[80:81]
	v_pk_add_f32 v[94:95], v[190:191], v[94:95]
	v_pk_add_f32 v[80:81], v[84:85], v[80:81]
	v_pk_add_f32 v[86:87], v[86:87], v[94:95]
	v_pk_add_f32 v[80:81], v[88:89], v[80:81]
	v_pk_add_f32 v[86:87], v[90:91], v[86:87]
	v_pk_add_f32 v[64:65], v[64:65], v[80:81]
	v_pk_add_f32 v[86:87], v[92:93], v[86:87]
	v_pk_add_f32 v[64:65], v[66:67], v[64:65]
	v_pk_add_f32 v[68:69], v[68:69], v[86:87]
	v_pk_add_f32 v[64:65], v[70:71], v[64:65]
	s_waitcnt lgkmcnt(0)
	s_barrier
	ds_read_b128 v[166:169], v199
	v_pk_add_f32 v[184:185], v[74:75], v[64:65]
	v_max_f32_e32 v64, v78, v78
	v_max_f32_e32 v65, v79, v79
	v_pk_add_f32 v[68:69], v[72:73], v[68:69]
	v_max_f32_e32 v64, v64, v65
	v_pk_add_f32 v[186:187], v[76:77], v[68:69]
	v_cmp_lt_f32_e32 vcc, s96, v64
	s_cbranch_vccz .LBB0_580
	v_max_f32_e32 v32, v64, v64
	v_max_f32_e32 v33, 0, v32
	v_exp_f32_e64 v34, -v33
	v_add_f32_e32 v209, v209, v33
	v_xor_b32_e32 v32, 0x80000000, v209
	v_sub_f32_e32 v127, v127, v33
	v_sub_f32_e32 v126, v126, v33
	v_sub_f32_e32 v125, v125, v33
	v_sub_f32_e32 v124, v124, v33
	v_sub_f32_e32 v123, v123, v33
	v_sub_f32_e32 v122, v122, v33
	v_sub_f32_e32 v121, v121, v33
	v_sub_f32_e32 v120, v120, v33
	v_sub_f32_e32 v119, v119, v33
	v_sub_f32_e32 v118, v118, v33
	v_sub_f32_e32 v117, v117, v33
	v_sub_f32_e32 v116, v116, v33
	v_sub_f32_e32 v115, v115, v33
	v_sub_f32_e32 v114, v114, v33
	v_sub_f32_e32 v113, v113, v33
	v_sub_f32_e32 v112, v112, v33
	v_sub_f32_e32 v111, v111, v33
	v_sub_f32_e32 v110, v110, v33
	v_sub_f32_e32 v109, v109, v33
	v_sub_f32_e32 v108, v108, v33
	v_sub_f32_e32 v107, v107, v33
	v_sub_f32_e32 v106, v106, v33
	v_sub_f32_e32 v105, v105, v33
	v_sub_f32_e32 v104, v104, v33
	v_sub_f32_e32 v103, v103, v33
	v_sub_f32_e32 v102, v102, v33
	v_sub_f32_e32 v101, v101, v33
	v_sub_f32_e32 v100, v100, v33
	v_sub_f32_e32 v99, v99, v33
	v_sub_f32_e32 v98, v98, v33
	v_sub_f32_e32 v97, v97, v33
	v_sub_f32_e32 v96, v96, v33
	v_pk_mul_f32 v[14:15], v[14:15], v[34:35] op_sel_hi:[1,0]
	v_pk_mul_f32 v[12:13], v[12:13], v[34:35] op_sel_hi:[1,0]
	v_pk_mul_f32 v[10:11], v[10:11], v[34:35] op_sel_hi:[1,0]
	v_pk_mul_f32 v[8:9], v[8:9], v[34:35] op_sel_hi:[1,0]
	v_pk_mul_f32 v[6:7], v[6:7], v[34:35] op_sel_hi:[1,0]
	v_pk_mul_f32 v[4:5], v[4:5], v[34:35] op_sel_hi:[1,0]
	v_pk_mul_f32 v[2:3], v[2:3], v[34:35] op_sel_hi:[1,0]
	v_pk_mul_f32 v[0:1], v[0:1], v[34:35] op_sel_hi:[1,0]
	v_pk_mul_f32 v[30:31], v[30:31], v[34:35] op_sel_hi:[1,0]
	v_pk_mul_f32 v[28:29], v[28:29], v[34:35] op_sel_hi:[1,0]
	v_pk_mul_f32 v[26:27], v[26:27], v[34:35] op_sel_hi:[1,0]
	v_pk_mul_f32 v[24:25], v[24:25], v[34:35] op_sel_hi:[1,0]
	v_pk_mul_f32 v[22:23], v[22:23], v[34:35] op_sel_hi:[1,0]
	v_pk_mul_f32 v[20:21], v[20:21], v[34:35] op_sel_hi:[1,0]
	v_pk_mul_f32 v[18:19], v[18:19], v[34:35] op_sel_hi:[1,0]
	v_pk_mul_f32 v[16:17], v[16:17], v[34:35] op_sel_hi:[1,0]
	v_pk_mul_f32 v[184:185], v[184:185], v[34:35] op_sel_hi:[1,0]
	v_pk_mul_f32 v[186:187], v[186:187], v[34:35] op_sel_hi:[1,0]
	v_mov_b32_e32 v33, v32
	v_mov_b32_e32 v34, v32
	v_mov_b32_e32 v35, v32
	v_mov_b32_e32 v36, v32
	v_mov_b32_e32 v37, v32
	v_mov_b32_e32 v38, v32
	v_mov_b32_e32 v39, v32
	v_mov_b32_e32 v40, v32
	v_mov_b32_e32 v41, v32
	v_mov_b32_e32 v42, v32
	v_mov_b32_e32 v43, v32
	v_mov_b32_e32 v44, v32
	v_mov_b32_e32 v45, v32
	v_mov_b32_e32 v46, v32
	v_mov_b32_e32 v47, v32
	v_mov_b32_e32 v48, v32
	v_mov_b32_e32 v49, v32
	v_mov_b32_e32 v50, v32
	v_mov_b32_e32 v51, v32
	v_mov_b32_e32 v52, v32
	v_mov_b32_e32 v53, v32
	v_mov_b32_e32 v54, v32
	v_mov_b32_e32 v55, v32
	v_mov_b32_e32 v56, v32
	v_mov_b32_e32 v57, v32
	v_mov_b32_e32 v58, v32
	v_mov_b32_e32 v59, v32
	v_mov_b32_e32 v60, v32
	v_mov_b32_e32 v61, v32
	v_mov_b32_e32 v62, v32
	v_mov_b32_e32 v63, v32
.LBB0_580:
.LBB0_582:
	ds_read_b128 v[174:177], v199 offset:4096
	s_add_u32 s4, s92, 0x15678000
	s_addc_u32 s5, s93, 0
	s_mov_b32 m0, s91
	s_nop 0
	global_load_lds_dwordx4 v164, s[4:5]
	s_waitcnt lgkmcnt(0)
	v_mfma_f32_32x32x16_bf16 v[80:95], v[166:169], v[132:135], v[32:47]
	ds_read_b128 v[68:71], v200
	ds_read_b128 v[180:183], v200 offset:4096
	s_setprio 1
	v_exp_f32_e32 v112, v112
	v_exp_f32_e32 v167, v113
	v_exp_f32_e32 v166, v114
	v_exp_f32_e32 v113, v115
	s_setprio 0
	s_add_u32 s4, s92, 0x16618300
	s_addc_u32 s5, s93, 0
	s_mov_b32 m0, s95
	s_nop 0
	global_load_lds_dwordx4 v160, s[4:5]
	s_waitcnt lgkmcnt(0)
	v_mfma_f32_32x32x16_bf16 v[80:95], v[68:71], v[128:131], v[80:95]
	ds_read_b128 v[188:191], v201
	ds_read_b128 v[192:195], v201 offset:4096
	s_setprio 1
	v_mfma_f32_32x32x16_bf16 v[64:79], v[174:177], v[132:135], v[32:47]
	v_exp_f32_e32 v114, v116
	v_exp_f32_e32 v169, v117
	v_exp_f32_e32 v168, v118
	v_exp_f32_e32 v115, v119
	s_setprio 0
	v_cvt_pk_bf16_f32 v174, v112, v167
	v_cvt_pk_bf16_f32 v175, v166, v113
	v_cvt_pk_bf16_f32 v176, v114, v169
	v_cvt_pk_bf16_f32 v177, v168, v115
	s_and_b64 vcc, exec, s[44:45]
	s_cbranch_vccnz .Lmy_a4_norope
	s_add_u32 s4, s92, 0x33b8500
	s_addc_u32 s5, s93, 0
	s_add_i32 m0, s43, 0xe000
	s_nop 0
	global_load_lds_dwordx4 v162, s[4:5]
